# P0 RMSNorm row loop: the 8 loop-invariant gain chunks are loaded once before the loop; the per-chunk in-loop loads and their vmcnt(0) waits (which also serialised on the preceding store) are removed
# speedup vs baseline: 1.0032x; 1.0032x over previous
; __device__ __forceinline__ unsigned pk2(float lo, float hi) { return pg8::cvt_pk_bf16(lo, hi); }
; __device__ __forceinline__ void rms_row_2048(const float* xrow, const float* g, bf16* orow, int lane) {
;     const f32x4* xr = (const f32x4*)xrow + lane; const f32x4* gr = (const f32x4*)g + lane;
;     f32x4 v[8]; float s = 0.f;
; #pragma unroll
;     for (int j = 0; j < 8; ++j) { v[j] = __builtin_nontemporal_load(xr + 64 * j); s += (v[j].x * v[j].x + v[j].y * v[j].y) + (v[j].z * v[j].z + v[j].w * v[j].w); }
;     const float r = rsqrtf(wave_sum(s) * (1.f / 2048.f) + EPS);
;     v2u* o8 = (v2u*)orow + lane;
; #pragma unroll
;     for (int j = 0; j < 8; ++j) { const f32x4 gg = gr[64 * j]; v2u o; o.x = pk2(v[j].x * r * gg.x, v[j].y * r * gg.y); o.y = pk2(v[j].z * r * gg.z, v[j].w * r * gg.w); o8[64 * j] = o; }
; }
; __global__ void __launch_bounds__(NWAVES * 64, 2) fwd_kernel(Args a) {
;     ...
;         for (int m = gw; m < MTOK; m += NGW) rms_row_2048(x + (size_t)m * DM, a.in[2], u1 + (size_t)m * DM, lane);
.LBB0_21:
	s_or_b64 exec, exec, s[0:1]
	s_cmpk_gt_i32 s3, 0x1fff
	v_mbcnt_lo_u32_b32 v147, -1, 0
	s_cbranch_scc1 .LBB0_24
	v_mbcnt_hi_u32_b32 v4, -1, v147
	v_lshlrev_b32_e32 v2, 4, v1
	v_and_b32_e32 v1, 64, v4
	v_add_u32_e32 v5, 64, v1
	v_xor_b32_e32 v1, 1, v4
	v_cmp_lt_i32_e32 vcc, v1, v5
	v_xor_b32_e32 v8, 2, v4
	s_ashr_i32 s7, s13, 31
	v_cndmask_b32_e32 v1, v4, v1, vcc
	v_cmp_lt_i32_e32 vcc, v8, v5
	s_ashr_i32 s8, s90, 31
	s_add_u32 s6, s13, s90
	v_cndmask_b32_e32 v8, v4, v8, vcc
	s_waitcnt vmcnt(19)
	v_lshlrev_b32_e32 v20, 2, v8
	v_xor_b32_e32 v8, 4, v4
	v_cmp_lt_i32_e32 vcc, v8, v5
	v_mov_b32_e32 v3, 0
	s_addc_u32 s7, s7, s8
	v_cndmask_b32_e32 v8, v4, v8, vcc
	v_lshlrev_b32_e32 v21, 2, v8
	v_xor_b32_e32 v8, 8, v4
	v_cmp_lt_i32_e32 vcc, v8, v5
	v_lshl_add_u64 v[6:7], s[56:57], 0, v[2:3]
	s_mov_b64 s[0:1], 0x1000
	v_cndmask_b32_e32 v8, v4, v8, vcc
	s_waitcnt vmcnt(18)
	v_lshlrev_b32_e32 v22, 2, v8
	v_xor_b32_e32 v8, 16, v4
	v_cmp_lt_i32_e32 vcc, v8, v5
	s_lshl_b64 s[8:9], s[6:7], 13
	s_add_u32 s8, s52, s8
	v_cndmask_b32_e32 v8, v4, v8, vcc
	v_lshlrev_b32_e32 v23, 2, v8
	v_xor_b32_e32 v8, 32, v4
	v_cmp_lt_i32_e32 vcc, v8, v5
	s_addc_u32 s9, s53, s9
	s_ashr_i32 s13, s12, 31
	v_cndmask_b32_e32 v4, v4, v8, vcc
	v_lshl_add_u64 v[8:9], v[6:7], 0, s[0:1]
	s_mov_b64 s[0:1], 0x1400
	v_lshl_add_u64 v[10:11], v[6:7], 0, s[0:1]
	s_mov_b64 s[0:1], 0x1800
	v_lshlrev_b32_e32 v24, 2, v4
	v_lshl_add_u64 v[12:13], v[6:7], 0, s[0:1]
	s_mov_b64 s[0:1], 0x1c00
	v_lshl_add_u64 v[4:5], s[8:9], 0, v[2:3]
	v_lshl_add_u64 v[14:15], v[6:7], 0, s[0:1]
	v_lshl_add_u64 v[16:17], v[4:5], 0, s[0:1]
	s_lshl_b64 s[0:1], s[12:13], 13
	s_lshl_b64 s[6:7], s[6:7], 12
	s_add_u32 s6, s30, s6
	v_mov_b32_e32 v131, v3
	s_addc_u32 s7, s31, s7
	v_lshl_add_u64 v[2:3], s[6:7], 0, v[130:131]
	s_mov_b64 s[6:7], 0x4200800
	v_lshlrev_b32_e32 v1, 2, v1
	v_lshl_add_u64 v[18:19], v[2:3], 0, s[6:7]
	s_lshl_b64 s[6:7], s[12:13], 12
	v_mov_b32_e32 v25, 0x358637bd
	s_mov_b32 s8, 0x800000
	global_load_dwordx4 v[176:179], v[6:7], off
	global_load_dwordx4 v[180:183], v[6:7], off offset:1024
	global_load_dwordx4 v[184:187], v[6:7], off offset:2048
	global_load_dwordx4 v[188:191], v[6:7], off offset:3072
	global_load_dwordx4 v[192:195], v[8:9], off
	global_load_dwordx4 v[196:199], v[10:11], off
	global_load_dwordx4 v[200:203], v[12:13], off
	global_load_dwordx4 v[204:207], v[14:15], off
; __device__ __forceinline__ unsigned pk2(float lo, float hi) { return pg8::cvt_pk_bf16(lo, hi); }
; __device__ __forceinline__ void rms_row_2048(const float* xrow, const float* g, bf16* orow, int lane) {
;     const f32x4* xr = (const f32x4*)xrow + lane; const f32x4* gr = (const f32x4*)g + lane;
;     f32x4 v[8]; float s = 0.f;
; #pragma unroll
;     for (int j = 0; j < 8; ++j) { v[j] = __builtin_nontemporal_load(xr + 64 * j); s += (v[j].x * v[j].x + v[j].y * v[j].y) + (v[j].z * v[j].z + v[j].w * v[j].w); }
;     const float r = rsqrtf(wave_sum(s) * (1.f / 2048.f) + EPS);
;     v2u* o8 = (v2u*)orow + lane;
; #pragma unroll
;     for (int j = 0; j < 8; ++j) { const f32x4 gg = gr[64 * j]; v2u o; o.x = pk2(v[j].x * r * gg.x, v[j].y * r * gg.y); o.y = pk2(v[j].z * r * gg.z, v[j].w * r * gg.w); o8[64 * j] = o; }
; }
.LBB0_23:
	global_load_dwordx4 v[26:29], v[16:17], off offset:-3072 nt
	global_load_dwordx4 v[30:33], v[16:17], off offset:-2048 nt
	global_load_dwordx4 v[2:5], v[16:17], off nt
	global_load_dwordx4 v[34:37], v[16:17], off offset:-1024 nt
	s_waitcnt vmcnt(19)
	v_add_co_u32_e32 v50, vcc, 0xfffff000, v16
	s_nop 0
	v_addc_co_u32_e32 v51, vcc, -1, v17, vcc
	global_load_dwordx4 v[42:45], v[50:51], off offset:-3072 nt
	global_load_dwordx4 v[46:49], v[50:51], off offset:-2048 nt
	s_nop 0
	global_load_dwordx4 v[50:53], v[50:51], off offset:-1024 nt
	s_nop 0
	global_load_dwordx4 v[54:57], v[16:17], off offset:-4096 nt
	s_add_i32 s3, s3, s12
	s_cmpk_gt_i32 s3, 0x1fff
	v_lshl_add_u64 v[16:17], v[16:17], 0, s[0:1]
	s_waitcnt vmcnt(7)
	v_mul_f32_e32 v81, v26, v26
	s_waitcnt vmcnt(6)
	v_pk_mul_f32 v[58:59], v[32:33], v[32:33]
	v_pk_mul_f32 v[60:61], v[30:31], v[30:31]
	s_waitcnt vmcnt(4)
	v_mul_f32_e32 v62, v35, v35
	v_mul_f32_e32 v64, v37, v37
	v_mul_f32_e32 v79, v4, v4
	v_mul_f32_e32 v87, v5, v5
	v_pk_mov_b32 v[66:67], v[60:61], v[58:59] op_sel:[1,0]
	v_mov_b32_e32 v61, v59
	v_pk_fma_f32 v[58:59], v[34:35], v[34:35], v[62:63] op_sel_hi:[1,1,0]
	v_pk_fma_f32 v[62:63], v[36:37], v[36:37], v[64:65] op_sel_hi:[1,1,0]
	s_waitcnt vmcnt(3)
	v_mov_b32_e32 v68, v43
	s_waitcnt vmcnt(2)
	v_mov_b32_e32 v69, v47
	v_mov_b32_e32 v72, v45
	v_mov_b32_e32 v73, v49
	v_mov_b32_e32 v64, v42
	v_mov_b32_e32 v65, v46
	v_mov_b32_e32 v70, v44
	v_mov_b32_e32 v71, v48
	s_waitcnt vmcnt(1)
	v_pk_mul_f32 v[74:75], v[52:53], v[52:53]
	v_pk_mul_f32 v[76:77], v[50:51], v[50:51]
	v_pk_add_f32 v[60:61], v[66:67], v[60:61]
	v_mov_b32_e32 v59, v79
	v_mov_b32_e32 v63, v87
	v_pk_mul_f32 v[66:67], v[68:69], v[68:69]
	v_pk_mul_f32 v[68:69], v[72:73], v[72:73]
	v_pk_mov_b32 v[72:73], v[76:77], v[74:75] op_sel:[1,0]
	v_mov_b32_e32 v77, v75
	v_pk_add_f32 v[58:59], v[58:59], v[62:63]
	v_pk_fma_f32 v[62:63], v[64:65], v[64:65], v[66:67]
	v_pk_fma_f32 v[64:65], v[70:71], v[70:71], v[68:69]
	s_waitcnt vmcnt(0)
	v_mul_f32_e32 v78, v55, v55
	v_mul_f32_e32 v80, v57, v57
	v_pk_add_f32 v[66:67], v[72:73], v[76:77]
	v_pk_add_f32 v[62:63], v[62:63], v[64:65]
	v_mul_f32_e32 v82, v27, v27
	v_mul_f32_e32 v83, v28, v28
	v_mul_f32_e32 v84, v29, v29
	v_pk_fma_f32 v[74:75], v[54:55], v[54:55], v[78:79] op_sel_hi:[1,1,0]
	v_pk_fma_f32 v[78:79], v[56:57], v[56:57], v[80:81] op_sel_hi:[1,1,0]
	v_pk_add_f32 v[64:65], v[66:67], v[66:67] op_sel:[0,1] op_sel_hi:[1,0]
	v_pk_add_f32 v[62:63], v[62:63], v[62:63] op_sel:[0,1] op_sel_hi:[1,0]
	v_mov_b32_e32 v75, v83
	v_mov_b32_e32 v79, v84
	v_mov_b32_e32 v65, v82
	v_mov_b32_e32 v63, v81
	v_pk_add_f32 v[66:67], v[74:75], v[78:79]
	v_pk_add_f32 v[62:63], v[62:63], v[64:65]
	v_mul_f32_e32 v85, v2, v2
	v_pk_add_f32 v[62:63], v[62:63], v[66:67]
	v_mul_f32_e32 v86, v3, v3
	v_pk_add_f32 v[60:61], v[60:61], v[60:61] op_sel:[0,1] op_sel_hi:[1,0]
	v_pk_add_f32 v[62:63], v[62:63], v[62:63] op_sel:[0,1] op_sel_hi:[1,0]
	v_mov_b32_e32 v61, v86
	v_mov_b32_e32 v63, v85
	v_pk_add_f32 v[60:61], v[62:63], v[60:61]
	s_nop 0
	v_pk_add_f32 v[58:59], v[60:61], v[58:59]
	s_nop 0
	v_add_f32_e32 v58, v58, v59
	ds_bpermute_b32 v59, v1, v58
	s_waitcnt lgkmcnt(0)
	v_add_f32_e32 v58, v58, v59
	ds_bpermute_b32 v59, v20, v58
	s_waitcnt lgkmcnt(0)
	v_add_f32_e32 v58, v58, v59
	ds_bpermute_b32 v59, v21, v58
	s_waitcnt lgkmcnt(0)
	v_add_f32_e32 v58, v58, v59
	ds_bpermute_b32 v59, v22, v58
	s_waitcnt lgkmcnt(0)
	v_add_f32_e32 v58, v58, v59
	ds_bpermute_b32 v59, v23, v58
	s_waitcnt lgkmcnt(0)
	v_add_f32_e32 v58, v58, v59
	ds_bpermute_b32 v59, v24, v58
	s_waitcnt lgkmcnt(0)
	v_add_f32_e32 v58, v58, v59
	v_fmamk_f32 v58, v58, 0x3a000000, v25
	v_mul_f32_e32 v59, 0x4b800000, v58
	v_cmp_gt_f32_e32 vcc, s8, v58
	s_nop 1
	v_cndmask_b32_e32 v58, v58, v59, vcc
	v_rsq_f32_e32 v58, v58
	s_nop 0
	v_mul_f32_e32 v59, 0x45800000, v58
	v_cndmask_b32_e32 v58, v58, v59, vcc
	v_mul_f32_e32 v42, v42, v58
	v_mul_f32_e32 v43, v43, v58
	v_mul_f32_e32 v44, v44, v58
	v_mul_f32_e32 v45, v45, v58
	v_mul_f32_e32 v38, v176, v42
	v_mul_f32_e32 v39, v177, v43
	v_mul_f32_e32 v40, v178, v44
	v_mul_f32_e32 v41, v179, v45
	v_cvt_pk_bf16_f32 v38, v38, v39
	v_cvt_pk_bf16_f32 v39, v40, v41
	global_store_dwordx2 v[18:19], v[38:39], off offset:-2048
	v_mul_f32_e32 v42, v46, v58
	v_mul_f32_e32 v43, v47, v58
	v_mul_f32_e32 v44, v48, v58
	v_mul_f32_e32 v45, v49, v58
	v_mul_f32_e32 v26, v26, v58
	v_mul_f32_e32 v27, v27, v58
	v_mul_f32_e32 v28, v28, v58
	v_mul_f32_e32 v29, v29, v58
	v_mul_f32_e32 v30, v30, v58
	v_mul_f32_e32 v31, v31, v58
	v_mul_f32_e32 v32, v32, v58
	v_mul_f32_e32 v33, v33, v58
	v_mul_f32_e32 v2, v2, v58
	v_mul_f32_e32 v3, v3, v58
	v_mul_f32_e32 v4, v4, v58
	v_mul_f32_e32 v5, v5, v58
	v_mul_f32_e32 v38, v180, v42
	v_mul_f32_e32 v39, v181, v43
	v_mul_f32_e32 v40, v182, v44
	v_mul_f32_e32 v41, v183, v45
	v_cvt_pk_bf16_f32 v38, v38, v39
	v_cvt_pk_bf16_f32 v39, v40, v41
	global_store_dwordx2 v[18:19], v[38:39], off offset:-1536
	v_mul_f32_e32 v42, v50, v58
	v_mul_f32_e32 v43, v51, v58
	v_mul_f32_e32 v44, v52, v58
	v_mul_f32_e32 v45, v53, v58
	v_mul_f32_e32 v38, v184, v42
	v_mul_f32_e32 v39, v185, v43
	v_mul_f32_e32 v40, v186, v44
	v_mul_f32_e32 v41, v187, v45
	v_cvt_pk_bf16_f32 v38, v38, v39
	v_cvt_pk_bf16_f32 v39, v40, v41
	global_store_dwordx2 v[18:19], v[38:39], off offset:-1024
	v_mul_f32_e32 v42, v54, v58
	v_mul_f32_e32 v43, v55, v58
	v_mul_f32_e32 v44, v56, v58
	v_mul_f32_e32 v45, v57, v58
	v_mul_f32_e32 v38, v42, v188
	v_mul_f32_e32 v39, v43, v189
	v_mul_f32_e32 v40, v44, v190
	v_mul_f32_e32 v41, v45, v191
	v_cvt_pk_bf16_f32 v38, v38, v39
	v_cvt_pk_bf16_f32 v39, v40, v41
	global_store_dwordx2 v[18:19], v[38:39], off offset:-512
	v_mul_f32_e32 v26, v26, v192
	v_mul_f32_e32 v27, v27, v193
	v_mul_f32_e32 v28, v28, v194
	v_mul_f32_e32 v29, v29, v195
	v_cvt_pk_bf16_f32 v26, v26, v27
	v_cvt_pk_bf16_f32 v27, v28, v29
	global_store_dwordx2 v[18:19], v[26:27], off
	v_mul_f32_e32 v26, v30, v196
	v_mul_f32_e32 v27, v31, v197
	v_mul_f32_e32 v28, v32, v198
	v_mul_f32_e32 v29, v33, v199
	v_cvt_pk_bf16_f32 v26, v26, v27
	v_cvt_pk_bf16_f32 v27, v28, v29
	global_store_dwordx2 v[18:19], v[26:27], off offset:512
	v_mul_f32_e32 v30, v34, v58
	v_mul_f32_e32 v31, v35, v58
	v_mul_f32_e32 v32, v36, v58
	v_mul_f32_e32 v33, v37, v58
	v_mul_f32_e32 v26, v30, v200
	v_mul_f32_e32 v27, v31, v201
	v_mul_f32_e32 v28, v32, v202
	v_mul_f32_e32 v29, v33, v203
	v_cvt_pk_bf16_f32 v26, v26, v27
	v_cvt_pk_bf16_f32 v27, v28, v29
	global_store_dwordx2 v[18:19], v[26:27], off offset:1024
	v_mul_f32_e32 v2, v2, v204
	v_mul_f32_e32 v3, v3, v205
	v_mul_f32_e32 v4, v4, v206
	v_mul_f32_e32 v5, v5, v207
	v_cvt_pk_bf16_f32 v2, v2, v3
	v_cvt_pk_bf16_f32 v3, v4, v5
	global_store_dwordx2 v[18:19], v[2:3], off offset:1536
	v_lshl_add_u64 v[18:19], v[18:19], 0, s[6:7]
	s_cbranch_scc0 .LBB0_23
